# GEMM tile epilogues: waves 4-7 run at s_setprio 1 (waves 0-3 drop back to 0 after their alignment barrier), reset at every K-loop iteration head
# speedup vs baseline: 1.0051x; 1.0044x over previous
; #define PG8_BAR __builtin_amdgcn_s_barrier()
; template <class Epi, bool ALIGN_EPI>
; __device__ __forceinline__ void gemm_phase(LAS unsigned char* lds, const int tid, const Gemm g, const StaticOrder& S, const Epi& E) {
;     ...
;         if constexpr (ALIGN_EPI) { if (wr == 0) PG8_BAR; }
;         E(acc, cur, wr, wc, fr, fq);
.LBB0_116:
	s_setprio 1
	s_and_b64 vcc, exec, s[14:15]
	s_cbranch_vccz .LBB0_118
	s_barrier
	s_setprio 0

; #define PG8_STAGE(bufoff, gbase, voff) do { _Pragma("unroll") for (int _i = 0; _i < 2; ++_i) \
;         __builtin_amdgcn_global_load_lds((const unsigned*)((const char*)(gbase) + (voff)[_i]), (LAS unsigned*)(lds + (bufoff) + ldsw + _i * 8192), 16, 0, 0); } while (0)
; #define PG8_LDA(dst, b, h) do { _Pragma("unroll") for (int m = 0; m < 4; ++m) _Pragma("unroll") for (int k = 0; k < 2; ++k) dst[m][k] = *(const LAS bf16x8*)(lds + PG8_SA(b, h) + aoff + m * 2048 + k * 1024); } while (0)
; #define PG8_LDB(dst, b, h) do { _Pragma("unroll") for (int n = 0; n < 2; ++n) _Pragma("unroll") for (int k = 0; k < 2; ++k) dst[n][k] = *(const LAS bf16x8*)(lds + PG8_SB(b, h) + boff + n * 2048 + k * 1024); } while (0)
; #define PG8_WAIT_V(n) asm volatile("s_waitcnt vmcnt(" #n ")" ::: "memory")
; #define PG8_WAIT_L(n) asm volatile("s_waitcnt lgkmcnt(" #n ")" ::: "memory")
; #define PG8_BAR __builtin_amdgcn_s_barrier()
; template <class Epi, bool ALIGN_EPI>
; __device__ __forceinline__ void gemm_phase(LAS unsigned char* lds, const int tid, const Gemm g, const StaticOrder& S, const Epi& E) {
;     ...
;         const bool has_next = S.next(ui + 1, nxt);
;         const char* nA = has_next ? (const char*)g.A + (size_t)nxt.pm * tstepA + PG8_KOFFA(nxt) : cA; const char* nB = has_next ? (const char*)g.Bt + (size_t)nxt.pn * tstepB + PG8_KOFFB(nxt) : cB;
;         const int nt = cur.ks >= 0 ? nt_split : nt_full;
;         for (int t = 0; t < nt; t += 2) {
;             if constexpr (Epi::HOOK) { if (t != 0 && (t & 7) == 0) E.hook(acc, cur, (t >> 3) - 1, wr, wc, fr, fq); }
;             const bool last = (t == nt - 2);
;             const char* a1 = cA + (size_t)(t + 1) * kstepA;
;             const char* a2 = last ? nA : cA + (size_t)(t + 2) * kstepA; const char* b2 = last ? nB : cB + (size_t)(t + 2) * kstepB;
;             const char* a3 = a2 + kstepA; const char* b3 = b2 + kstepB;
;             PG8_LDB(B0, 0, 0); PG8_LDB(B1, 0, 1); PG8_SCHED; PG8_LDA(At, 0, 0); PG8_STAGE(PG8_SA(1, 1), a1 + hstepA, voffA);
;             PG8_WAIT_V(8); PG8_WAIT_L(0); PG8_BAR; PG8_MMA(0, 0, At, B0); PG8_MMA(0, 1, At, B1); PG8_BAR; PG8_SCHED;
;             PG8_LDA(At, 0, 1); PG8_STAGE(PG8_SB(0, 0), b2, voffB); PG8_STAGE(PG8_SB(0, 1), b2 + hstepB, voffB); PG8_STAGE(PG8_SA(0, 0), a2, voffA);
;             PG8_WAIT_V(8); PG8_WAIT_L(0); PG8_BAR; PG8_MMA(1, 0, At, B0); PG8_MMA(1, 1, At, B1); PG8_BAR; PG8_SCHED;
.LBB0_143:
	s_setprio 0
	s_add_u32 s26, s24, 0xfff80080
	s_addc_u32 s27, s25, -1
	s_add_i32 s68, 0, 0x10000
	s_cmp_eq_u32 s67, 28
	s_cselect_b32 s29, s19, s27
	s_cselect_b32 s28, s18, s26
	v_add_u32_e32 v142, s68, v145
	s_cselect_b32 s27, s21, s17
	s_cselect_b32 s26, s20, s15
	s_add_i32 s70, 0, 0x14000
	ds_read_b128 v[148:151], v142
	ds_read_b128 v[152:155], v142 offset:1024
	ds_read_b128 v[156:159], v142 offset:2048
	ds_read_b128 v[160:163], v142 offset:3072
	v_add_u32_e32 v142, s70, v145
	ds_read_b128 v[164:167], v142
	ds_read_b128 v[168:171], v142 offset:1024
	ds_read_b128 v[172:175], v142 offset:2048
	ds_read_b128 v[176:179], v142 offset:3072
	v_lshl_add_u64 v[142:143], s[24:25], 0, v[140:141]
	s_add_i32 m0, s23, 0xc000
	ds_read_b128 v[180:183], v146
	ds_read_b128 v[184:187], v146 offset:1024
	ds_read_b128 v[188:191], v146 offset:2048
	ds_read_b128 v[192:195], v146 offset:3072
	ds_read_b128 v[210:213], v146 offset:4096
	ds_read_b128 v[214:217], v146 offset:5120
	ds_read_b128 v[218:221], v146 offset:6144
	ds_read_b128 v[222:225], v146 offset:7168
	global_load_lds_dwordx4 v[142:143], off
	v_lshl_add_u64 v[142:143], s[24:25], 0, v[138:139]
	s_add_i32 m0, s23, 0xe000
	s_nop 0
	global_load_lds_dwordx4 v[142:143], off
	s_sub_u32 s98, s24, 0x80000
	s_subb_u32 s99, s25, 0
	v_lshl_add_u64 v[142:143], s[98:99], 0, v[140:141]
	s_mov_b32 m0, s56
	s_nop 0
	global_load_lds_dwordx4 v[142:143], off
	v_lshl_add_u64 v[142:143], s[98:99], 0, v[138:139]
	s_mov_b32 m0, s58
	s_nop 0
	global_load_lds_dwordx4 v[142:143], off
	s_waitcnt vmcnt(8)
	s_waitcnt lgkmcnt(0)
	s_barrier
	v_mfma_f32_16x16x32_bf16 v[126:129], v[148:151], v[180:183], v[126:129]
	v_mfma_f32_16x16x32_bf16 v[122:125], v[156:159], v[180:183], v[122:125]
	v_mfma_f32_16x16x32_bf16 v[110:113], v[148:151], v[188:191], v[110:113]
	v_mfma_f32_16x16x32_bf16 v[106:109], v[156:159], v[188:191], v[106:109]
	v_mfma_f32_16x16x32_bf16 v[94:97], v[148:151], v[210:213], v[94:97]
	v_mfma_f32_16x16x32_bf16 v[90:93], v[156:159], v[210:213], v[90:93]
	v_mfma_f32_16x16x32_bf16 v[78:81], v[148:151], v[218:221], v[78:81]
	v_mfma_f32_16x16x32_bf16 v[74:77], v[156:159], v[218:221], v[74:77]
	v_mfma_f32_16x16x32_bf16 v[126:129], v[152:155], v[184:187], v[126:129]
	v_mfma_f32_16x16x32_bf16 v[122:125], v[160:163], v[184:187], v[122:125]
	v_mfma_f32_16x16x32_bf16 v[110:113], v[152:155], v[192:195], v[110:113]
	v_mfma_f32_16x16x32_bf16 v[106:109], v[160:163], v[192:195], v[106:109]
	v_mfma_f32_16x16x32_bf16 v[94:97], v[152:155], v[214:217], v[94:97]
	v_mfma_f32_16x16x32_bf16 v[90:93], v[160:163], v[214:217], v[90:93]
	v_mfma_f32_16x16x32_bf16 v[78:81], v[152:155], v[222:225], v[78:81]
	v_mfma_f32_16x16x32_bf16 v[74:77], v[160:163], v[222:225], v[74:77]
	v_mfma_f32_16x16x32_bf16 v[118:121], v[164:167], v[180:183], v[118:121]
	v_mfma_f32_16x16x32_bf16 v[114:117], v[172:175], v[180:183], v[114:117]
	v_mfma_f32_16x16x32_bf16 v[102:105], v[164:167], v[188:191], v[102:105]
	v_mfma_f32_16x16x32_bf16 v[98:101], v[172:175], v[188:191], v[98:101]
	v_mfma_f32_16x16x32_bf16 v[86:89], v[164:167], v[210:213], v[86:89]
	v_mfma_f32_16x16x32_bf16 v[82:85], v[172:175], v[210:213], v[82:85]
	v_mfma_f32_16x16x32_bf16 v[70:73], v[164:167], v[218:221], v[70:73]
	v_mfma_f32_16x16x32_bf16 v[66:69], v[172:175], v[218:221], v[66:69]
	v_mfma_f32_16x16x32_bf16 v[118:121], v[168:171], v[184:187], v[118:121]
	v_mfma_f32_16x16x32_bf16 v[114:117], v[176:179], v[184:187], v[114:117]
	v_mfma_f32_16x16x32_bf16 v[102:105], v[168:171], v[192:195], v[102:105]
	v_mfma_f32_16x16x32_bf16 v[98:101], v[176:179], v[192:195], v[98:101]
	v_mfma_f32_16x16x32_bf16 v[86:89], v[168:171], v[214:217], v[86:89]
	v_mfma_f32_16x16x32_bf16 v[82:85], v[176:179], v[214:217], v[82:85]
	v_mfma_f32_16x16x32_bf16 v[70:73], v[168:171], v[222:225], v[70:73]
	v_mfma_f32_16x16x32_bf16 v[66:69], v[176:179], v[222:225], v[66:69]
	s_barrier
	s_add_i32 s68, s68, s30
	v_lshl_add_u64 v[142:143], s[26:27], 0, v[0:1]
	s_mov_b32 m0, s68
	ds_read_b128 v[180:183], v146 offset:16384
	ds_read_b128 v[184:187], v146 offset:17408
	ds_read_b128 v[188:191], v146 offset:18432
	ds_read_b128 v[192:195], v146 offset:19456
	ds_read_b128 v[210:213], v146 offset:20480
	ds_read_b128 v[214:217], v146 offset:21504
	ds_read_b128 v[218:221], v146 offset:22528
	ds_read_b128 v[222:225], v146 offset:23552
	global_load_lds_dwordx4 v[142:143], off
	s_add_i32 m0, s68, 0x2000
	s_add_u32 s68, s26, 0x80000
	v_lshl_add_u64 v[240:241], s[26:27], 0, v[130:131]
	s_addc_u32 s69, s27, 0
	s_add_i32 s70, s70, s30
	global_load_lds_dwordx4 v[240:241], off
	v_lshl_add_u64 v[242:243], s[68:69], 0, v[0:1]
	s_mov_b32 m0, s70
	v_lshl_add_u64 v[244:245], s[28:29], 0, v[132:133]
	global_load_lds_dwordx4 v[242:243], off
	v_lshl_add_u64 v[242:243], s[68:69], 0, v[130:131]
	s_add_i32 m0, s70, 0x2000
	s_nop 0
	global_load_lds_dwordx4 v[242:243], off
	v_lshl_add_u64 v[242:243], s[28:29], 0, v[134:135]
	s_waitcnt vmcnt(4)
	s_waitcnt lgkmcnt(0)
	s_barrier
; #define PG8_STAGE(bufoff, gbase, voff) do { _Pragma("unroll") for (int _i = 0; _i < 2; ++_i) \
;         __builtin_amdgcn_global_load_lds((const unsigned*)((const char*)(gbase) + (voff)[_i]), (LAS unsigned*)(lds + (bufoff) + ldsw + _i * 8192), 16, 0, 0); } while (0)
; #define PG8_LDA(dst, b, h) do { _Pragma("unroll") for (int m = 0; m < 4; ++m) _Pragma("unroll") for (int k = 0; k < 2; ++k) dst[m][k] = *(const LAS bf16x8*)(lds + PG8_SA(b, h) + aoff + m * 2048 + k * 1024); } while (0)
; #define PG8_LDB(dst, b, h) do { _Pragma("unroll") for (int n = 0; n < 2; ++n) _Pragma("unroll") for (int k = 0; k < 2; ++k) dst[n][k] = *(const LAS bf16x8*)(lds + PG8_SB(b, h) + boff + n * 2048 + k * 1024); } while (0)
; #define PG8_MMA(ai, bj, At, Bt) do { __builtin_amdgcn_s_setprio(1); _Pragma("unroll") for (int m = 0; m < 4; ++m) _Pragma("unroll") for (int n = 0; n < 2; ++n) _Pragma("unroll") for (int k = 0; k < 2; ++k) \
;         acc[ai][bj][m][n] = __builtin_amdgcn_mfma_f32_16x16x32_bf16(Bt[n][k], At[m][k], acc[ai][bj][m][n], 0, 0, 0); __builtin_amdgcn_s_setprio(0); } while (0)
; #define PG8_WAIT_V(n) asm volatile("s_waitcnt vmcnt(" #n ")" ::: "memory")
; #define PG8_WAIT_L(n) asm volatile("s_waitcnt lgkmcnt(" #n ")" ::: "memory")
; #define PG8_BAR __builtin_amdgcn_s_barrier()
; #define PG8_SCHED __builtin_amdgcn_sched_barrier(0)
; template <class Epi, bool ALIGN_EPI>
; __device__ __forceinline__ void gemm_phase(LAS unsigned char* lds, const int tid, const Gemm g, const StaticOrder& S, const Epi& E) {
;     ...
;             PG8_WAIT_V(8); PG8_WAIT_L(0); PG8_BAR; PG8_MMA(1, 0, At, B0); PG8_MMA(1, 1, At, B1); PG8_BAR; PG8_SCHED;
;             PG8_LDB(B0, 1, 0); PG8_LDB(B1, 1, 1); PG8_SCHED; PG8_LDA(At, 1, 0); PG8_STAGE(PG8_SA(0, 1), a2 + hstepA, voffA);
;             PG8_WAIT_V(8); PG8_WAIT_L(0); PG8_BAR; PG8_MMA(0, 0, At, B0); PG8_MMA(0, 1, At, B1); PG8_BAR; PG8_SCHED;
	v_mfma_f32_16x16x32_bf16 v[62:65], v[148:151], v[180:183], v[62:65]
	v_mfma_f32_16x16x32_bf16 v[58:61], v[156:159], v[180:183], v[58:61]
	v_mfma_f32_16x16x32_bf16 v[46:49], v[148:151], v[188:191], v[46:49]
	v_mfma_f32_16x16x32_bf16 v[42:45], v[156:159], v[188:191], v[42:45]
	v_mfma_f32_16x16x32_bf16 v[30:33], v[148:151], v[210:213], v[30:33]
	v_mfma_f32_16x16x32_bf16 v[26:29], v[156:159], v[210:213], v[26:29]
	v_mfma_f32_16x16x32_bf16 v[14:17], v[148:151], v[218:221], v[14:17]
	v_mfma_f32_16x16x32_bf16 v[10:13], v[156:159], v[218:221], v[10:13]
	v_mfma_f32_16x16x32_bf16 v[62:65], v[152:155], v[184:187], v[62:65]
	v_mfma_f32_16x16x32_bf16 v[58:61], v[160:163], v[184:187], v[58:61]
	v_mfma_f32_16x16x32_bf16 v[46:49], v[152:155], v[192:195], v[46:49]
	v_mfma_f32_16x16x32_bf16 v[42:45], v[160:163], v[192:195], v[42:45]
	v_mfma_f32_16x16x32_bf16 v[30:33], v[152:155], v[214:217], v[30:33]
	v_mfma_f32_16x16x32_bf16 v[26:29], v[160:163], v[214:217], v[26:29]
	v_mfma_f32_16x16x32_bf16 v[14:17], v[152:155], v[222:225], v[14:17]
	v_mfma_f32_16x16x32_bf16 v[10:13], v[160:163], v[222:225], v[10:13]
	v_mfma_f32_16x16x32_bf16 v[54:57], v[164:167], v[180:183], v[54:57]
	v_mfma_f32_16x16x32_bf16 v[50:53], v[172:175], v[180:183], v[50:53]
	v_mfma_f32_16x16x32_bf16 v[38:41], v[164:167], v[188:191], v[38:41]
	v_mfma_f32_16x16x32_bf16 v[34:37], v[172:175], v[188:191], v[34:37]
	v_mfma_f32_16x16x32_bf16 v[22:25], v[164:167], v[210:213], v[22:25]
	v_mfma_f32_16x16x32_bf16 v[18:21], v[172:175], v[210:213], v[18:21]
	v_mfma_f32_16x16x32_bf16 v[6:9], v[164:167], v[218:221], v[6:9]
	v_mfma_f32_16x16x32_bf16 v[2:5], v[172:175], v[218:221], v[2:5]
	v_mfma_f32_16x16x32_bf16 v[54:57], v[168:171], v[184:187], v[54:57]
	v_mfma_f32_16x16x32_bf16 v[50:53], v[176:179], v[184:187], v[50:53]
	v_mfma_f32_16x16x32_bf16 v[38:41], v[168:171], v[192:195], v[38:41]
	v_mfma_f32_16x16x32_bf16 v[34:37], v[176:179], v[192:195], v[34:37]
	v_mfma_f32_16x16x32_bf16 v[22:25], v[168:171], v[214:217], v[22:25]
	v_mfma_f32_16x16x32_bf16 v[18:21], v[176:179], v[214:217], v[18:21]
	v_mfma_f32_16x16x32_bf16 v[6:9], v[168:171], v[222:225], v[6:9]
	v_mfma_f32_16x16x32_bf16 v[2:5], v[176:179], v[222:225], v[2:5]
	s_barrier
	s_add_i32 s68, 0, 0x18000
	v_add_u32_e32 v147, s68, v145
	s_add_i32 s69, 0, 0x1c000
	ds_read_b128 v[148:151], v147
	ds_read_b128 v[152:155], v147 offset:1024
	ds_read_b128 v[156:159], v147 offset:2048
	ds_read_b128 v[160:163], v147 offset:3072
	v_add_u32_e32 v147, s69, v145
	ds_read_b128 v[164:167], v147
	ds_read_b128 v[168:171], v147 offset:1024
	ds_read_b128 v[172:175], v147 offset:2048
	ds_read_b128 v[176:179], v147 offset:3072
	s_mov_b32 m0, s23
	s_nop 0
	global_load_lds_dwordx4 v[242:243], off
	s_mov_b32 m0, s52
	s_nop 0
	global_load_lds_dwordx4 v[244:245], off
	s_add_u32 s28, s28, 0x80000
	s_addc_u32 s29, s29, 0
	s_mov_b32 m0, s54
	v_lshl_add_u64 v[246:247], s[28:29], 0, v[134:135]
	ds_read_b128 v[180:183], v146 offset:32768
	ds_read_b128 v[184:187], v146 offset:33792
	ds_read_b128 v[188:191], v146 offset:34816
	ds_read_b128 v[192:195], v146 offset:35840
	ds_read_b128 v[210:213], v146 offset:36864
	ds_read_b128 v[214:217], v146 offset:37888
	ds_read_b128 v[218:221], v146 offset:38912
	ds_read_b128 v[222:225], v146 offset:39936
	global_load_lds_dwordx4 v[246:247], off
	v_lshl_add_u64 v[246:247], s[28:29], 0, v[132:133]
	s_mov_b32 m0, s55
	s_nop 0
	global_load_lds_dwordx4 v[246:247], off
	s_waitcnt vmcnt(8)
	s_waitcnt lgkmcnt(0)
	s_barrier
; #define PG8_STAGE(bufoff, gbase, voff) do { _Pragma("unroll") for (int _i = 0; _i < 2; ++_i) \
;         __builtin_amdgcn_global_load_lds((const unsigned*)((const char*)(gbase) + (voff)[_i]), (LAS unsigned*)(lds + (bufoff) + ldsw + _i * 8192), 16, 0, 0); } while (0)
; #define PG8_LDA(dst, b, h) do { _Pragma("unroll") for (int m = 0; m < 4; ++m) _Pragma("unroll") for (int k = 0; k < 2; ++k) dst[m][k] = *(const LAS bf16x8*)(lds + PG8_SA(b, h) + aoff + m * 2048 + k * 1024); } while (0)
; #define PG8_MMA(ai, bj, At, Bt) do { __builtin_amdgcn_s_setprio(1); _Pragma("unroll") for (int m = 0; m < 4; ++m) _Pragma("unroll") for (int n = 0; n < 2; ++n) _Pragma("unroll") for (int k = 0; k < 2; ++k) \
;         acc[ai][bj][m][n] = __builtin_amdgcn_mfma_f32_16x16x32_bf16(Bt[n][k], At[m][k], acc[ai][bj][m][n], 0, 0, 0); __builtin_amdgcn_s_setprio(0); } while (0)
; #define PG8_WAIT_V(n) asm volatile("s_waitcnt vmcnt(" #n ")" ::: "memory")
; #define PG8_WAIT_L(n) asm volatile("s_waitcnt lgkmcnt(" #n ")" ::: "memory")
; #define PG8_BAR __builtin_amdgcn_s_barrier()
; #define PG8_SCHED __builtin_amdgcn_sched_barrier(0)
; template <class Epi, bool ALIGN_EPI>
; __device__ __forceinline__ void gemm_phase(LAS unsigned char* lds, const int tid, const Gemm g, const StaticOrder& S, const Epi& E) {
;     ...
;             PG8_WAIT_V(8); PG8_WAIT_L(0); PG8_BAR; PG8_MMA(0, 0, At, B0); PG8_MMA(0, 1, At, B1); PG8_BAR; PG8_SCHED;
;             PG8_LDA(At, 1, 1); PG8_STAGE(PG8_SB(1, 0), b3, voffB); PG8_STAGE(PG8_SB(1, 1), b3 + hstepB, voffB); PG8_STAGE(PG8_SA(1, 0), a3, voffA);
;             PG8_WAIT_V(8); PG8_WAIT_L(0); PG8_BAR; PG8_MMA(1, 0, At, B0); PG8_MMA(1, 1, At, B1); PG8_BAR; PG8_SCHED;
;         }
;         if constexpr (ALIGN_EPI) { if (wr == 0) PG8_BAR; }
;         E(acc, cur, wr, wc, fr, fq);
	v_mfma_f32_16x16x32_bf16 v[126:129], v[148:151], v[180:183], v[126:129]
	v_mfma_f32_16x16x32_bf16 v[122:125], v[156:159], v[180:183], v[122:125]
	v_mfma_f32_16x16x32_bf16 v[110:113], v[148:151], v[188:191], v[110:113]
	v_mfma_f32_16x16x32_bf16 v[106:109], v[156:159], v[188:191], v[106:109]
	v_mfma_f32_16x16x32_bf16 v[94:97], v[148:151], v[210:213], v[94:97]
	v_mfma_f32_16x16x32_bf16 v[90:93], v[156:159], v[210:213], v[90:93]
	v_mfma_f32_16x16x32_bf16 v[78:81], v[148:151], v[218:221], v[78:81]
	v_mfma_f32_16x16x32_bf16 v[74:77], v[156:159], v[218:221], v[74:77]
	v_mfma_f32_16x16x32_bf16 v[126:129], v[152:155], v[184:187], v[126:129]
	v_mfma_f32_16x16x32_bf16 v[122:125], v[160:163], v[184:187], v[122:125]
	v_mfma_f32_16x16x32_bf16 v[110:113], v[152:155], v[192:195], v[110:113]
	v_mfma_f32_16x16x32_bf16 v[106:109], v[160:163], v[192:195], v[106:109]
	v_mfma_f32_16x16x32_bf16 v[94:97], v[152:155], v[214:217], v[94:97]
	v_mfma_f32_16x16x32_bf16 v[90:93], v[160:163], v[214:217], v[90:93]
	v_mfma_f32_16x16x32_bf16 v[78:81], v[152:155], v[222:225], v[78:81]
	v_mfma_f32_16x16x32_bf16 v[74:77], v[160:163], v[222:225], v[74:77]
	v_mfma_f32_16x16x32_bf16 v[118:121], v[164:167], v[180:183], v[118:121]
	v_mfma_f32_16x16x32_bf16 v[114:117], v[172:175], v[180:183], v[114:117]
	v_mfma_f32_16x16x32_bf16 v[102:105], v[164:167], v[188:191], v[102:105]
	v_mfma_f32_16x16x32_bf16 v[98:101], v[172:175], v[188:191], v[98:101]
	v_mfma_f32_16x16x32_bf16 v[86:89], v[164:167], v[210:213], v[86:89]
	v_mfma_f32_16x16x32_bf16 v[82:85], v[172:175], v[210:213], v[82:85]
	v_mfma_f32_16x16x32_bf16 v[70:73], v[164:167], v[218:221], v[70:73]
	v_mfma_f32_16x16x32_bf16 v[66:69], v[172:175], v[218:221], v[66:69]
	v_mfma_f32_16x16x32_bf16 v[118:121], v[168:171], v[184:187], v[118:121]
	v_mfma_f32_16x16x32_bf16 v[114:117], v[176:179], v[184:187], v[114:117]
	v_mfma_f32_16x16x32_bf16 v[102:105], v[168:171], v[192:195], v[102:105]
	v_mfma_f32_16x16x32_bf16 v[98:101], v[176:179], v[192:195], v[98:101]
	v_mfma_f32_16x16x32_bf16 v[86:89], v[168:171], v[214:217], v[86:89]
	v_mfma_f32_16x16x32_bf16 v[82:85], v[176:179], v[214:217], v[82:85]
	v_mfma_f32_16x16x32_bf16 v[70:73], v[168:171], v[222:225], v[70:73]
	v_mfma_f32_16x16x32_bf16 v[66:69], v[176:179], v[222:225], v[66:69]
	s_barrier
	s_add_i32 s28, s68, s30
	v_lshl_add_u64 v[142:143], v[142:143], 0, s[42:43]
	s_mov_b32 m0, s28
	ds_read_b128 v[180:183], v146 offset:49152
	ds_read_b128 v[184:187], v146 offset:50176
	ds_read_b128 v[188:191], v146 offset:51200
	ds_read_b128 v[192:195], v146 offset:52224
	ds_read_b128 v[210:213], v146 offset:53248
	ds_read_b128 v[214:217], v146 offset:54272
	ds_read_b128 v[218:221], v146 offset:55296
	ds_read_b128 v[222:225], v146 offset:56320
	global_load_lds_dwordx4 v[142:143], off
	s_add_i32 m0, s28, 0x2000
	s_add_u32 s26, s26, 0x80080
	v_lshl_add_u64 v[142:143], v[240:241], 0, s[42:43]
	s_addc_u32 s27, s27, 0
	s_add_i32 s28, s69, s30
	global_load_lds_dwordx4 v[142:143], off
	v_lshl_add_u64 v[142:143], s[26:27], 0, v[0:1]
	s_mov_b32 m0, s28
	s_nop 0
	global_load_lds_dwordx4 v[142:143], off
	v_lshl_add_u64 v[142:143], s[26:27], 0, v[130:131]
	s_add_i32 m0, s28, 0x2000
	s_nop 0
	global_load_lds_dwordx4 v[142:143], off
	s_waitcnt vmcnt(4)
	s_waitcnt lgkmcnt(0)
	s_barrier
	v_mfma_f32_16x16x32_bf16 v[62:65], v[148:151], v[180:183], v[62:65]
	v_mfma_f32_16x16x32_bf16 v[58:61], v[156:159], v[180:183], v[58:61]
	v_mfma_f32_16x16x32_bf16 v[46:49], v[148:151], v[188:191], v[46:49]
	v_mfma_f32_16x16x32_bf16 v[42:45], v[156:159], v[188:191], v[42:45]
	v_mfma_f32_16x16x32_bf16 v[30:33], v[148:151], v[210:213], v[30:33]
	v_mfma_f32_16x16x32_bf16 v[26:29], v[156:159], v[210:213], v[26:29]
	v_mfma_f32_16x16x32_bf16 v[14:17], v[148:151], v[218:221], v[14:17]
	v_mfma_f32_16x16x32_bf16 v[10:13], v[156:159], v[218:221], v[10:13]
	v_mfma_f32_16x16x32_bf16 v[62:65], v[152:155], v[184:187], v[62:65]
	v_mfma_f32_16x16x32_bf16 v[58:61], v[160:163], v[184:187], v[58:61]
	v_mfma_f32_16x16x32_bf16 v[46:49], v[152:155], v[192:195], v[46:49]
	v_mfma_f32_16x16x32_bf16 v[42:45], v[160:163], v[192:195], v[42:45]
	v_mfma_f32_16x16x32_bf16 v[30:33], v[152:155], v[214:217], v[30:33]
	v_mfma_f32_16x16x32_bf16 v[26:29], v[160:163], v[214:217], v[26:29]
	v_mfma_f32_16x16x32_bf16 v[14:17], v[152:155], v[222:225], v[14:17]
	v_mfma_f32_16x16x32_bf16 v[10:13], v[160:163], v[222:225], v[10:13]
	v_mfma_f32_16x16x32_bf16 v[54:57], v[164:167], v[180:183], v[54:57]
	v_mfma_f32_16x16x32_bf16 v[50:53], v[172:175], v[180:183], v[50:53]
	v_mfma_f32_16x16x32_bf16 v[38:41], v[164:167], v[188:191], v[38:41]
	v_mfma_f32_16x16x32_bf16 v[34:37], v[172:175], v[188:191], v[34:37]
	v_mfma_f32_16x16x32_bf16 v[22:25], v[164:167], v[210:213], v[22:25]
	v_mfma_f32_16x16x32_bf16 v[18:21], v[172:175], v[210:213], v[18:21]
	v_mfma_f32_16x16x32_bf16 v[6:9], v[164:167], v[218:221], v[6:9]
	v_mfma_f32_16x16x32_bf16 v[2:5], v[172:175], v[218:221], v[2:5]
	v_mfma_f32_16x16x32_bf16 v[54:57], v[168:171], v[184:187], v[54:57]
	v_mfma_f32_16x16x32_bf16 v[50:53], v[176:179], v[184:187], v[50:53]
	v_mfma_f32_16x16x32_bf16 v[38:41], v[168:171], v[192:195], v[38:41]
	v_mfma_f32_16x16x32_bf16 v[34:37], v[176:179], v[192:195], v[34:37]
	v_mfma_f32_16x16x32_bf16 v[22:25], v[168:171], v[214:217], v[22:25]
	v_mfma_f32_16x16x32_bf16 v[18:21], v[176:179], v[214:217], v[18:21]
	v_mfma_f32_16x16x32_bf16 v[6:9], v[168:171], v[222:225], v[6:9]
	v_mfma_f32_16x16x32_bf16 v[2:5], v[176:179], v[222:225], v[2:5]
	s_barrier
	s_add_i32 s67, s67, 2
	s_add_u32 s15, s15, 0x100
	s_addc_u32 s17, s17, 0
	s_add_u32 s24, s24, 0x100
	s_addc_u32 s25, s25, 0
	s_cmp_gt_u32 s67, 29
	s_cbranch_scc0 .LBB0_143
	s_setprio 1
	s_and_b64 vcc, exec, s[12:13]
	s_cbranch_vccz .LBB0_146
	s_barrier
	s_setprio 0

; #define PG8_STAGE(bufoff, gbase, voff) do { _Pragma("unroll") for (int _i = 0; _i < 2; ++_i) \
;         __builtin_amdgcn_global_load_lds((const unsigned*)((const char*)(gbase) + (voff)[_i]), (LAS unsigned*)(lds + (bufoff) + ldsw + _i * 8192), 16, 0, 0); } while (0)
; #define PG8_LDA(dst, b, h) do { _Pragma("unroll") for (int m = 0; m < 4; ++m) _Pragma("unroll") for (int k = 0; k < 2; ++k) dst[m][k] = *(const LAS bf16x8*)(lds + PG8_SA(b, h) + aoff + m * 2048 + k * 1024); } while (0)
; #define PG8_LDB(dst, b, h) do { _Pragma("unroll") for (int n = 0; n < 2; ++n) _Pragma("unroll") for (int k = 0; k < 2; ++k) dst[n][k] = *(const LAS bf16x8*)(lds + PG8_SB(b, h) + boff + n * 2048 + k * 1024); } while (0)
; #define PG8_WAIT_V(n) asm volatile("s_waitcnt vmcnt(" #n ")" ::: "memory")
; #define PG8_WAIT_L(n) asm volatile("s_waitcnt lgkmcnt(" #n ")" ::: "memory")
; #define PG8_BAR __builtin_amdgcn_s_barrier()
; template <class Epi, bool ALIGN_EPI>
; __device__ __forceinline__ void gemm_phase(LAS unsigned char* lds, const int tid, const Gemm g, const StaticOrder& S, const Epi& E) {
;     ...
;         const bool has_next = S.next(ui + 1, nxt);
;         const char* nA = has_next ? (const char*)g.A + (size_t)nxt.pm * tstepA + PG8_KOFFA(nxt) : cA; const char* nB = has_next ? (const char*)g.Bt + (size_t)nxt.pn * tstepB + PG8_KOFFB(nxt) : cB;
;         const int nt = cur.ks >= 0 ? nt_split : nt_full;
;         for (int t = 0; t < nt; t += 2) {
;             if constexpr (Epi::HOOK) { if (t != 0 && (t & 7) == 0) E.hook(acc, cur, (t >> 3) - 1, wr, wc, fr, fq); }
;             const bool last = (t == nt - 2);
;             const char* a1 = cA + (size_t)(t + 1) * kstepA;
;             const char* a2 = last ? nA : cA + (size_t)(t + 2) * kstepA; const char* b2 = last ? nB : cB + (size_t)(t + 2) * kstepB;
;             const char* a3 = a2 + kstepA; const char* b3 = b2 + kstepB;
;             PG8_LDB(B0, 0, 0); PG8_LDB(B1, 0, 1); PG8_SCHED; PG8_LDA(At, 0, 0); PG8_STAGE(PG8_SA(1, 1), a1 + hstepA, voffA);
;             PG8_WAIT_V(8); PG8_WAIT_L(0); PG8_BAR; PG8_MMA(0, 0, At, B0); PG8_MMA(0, 1, At, B1); PG8_BAR; PG8_SCHED;
;             PG8_LDA(At, 0, 1); PG8_STAGE(PG8_SB(0, 0), b2, voffB); PG8_STAGE(PG8_SB(0, 1), b2 + hstepB, voffB); PG8_STAGE(PG8_SA(0, 0), a2, voffA);
;             PG8_WAIT_V(8); PG8_WAIT_L(0); PG8_BAR; PG8_MMA(1, 0, At, B0); PG8_MMA(1, 1, At, B1); PG8_BAR; PG8_SCHED;
.LBB0_209:
	s_setprio 0
	s_add_i32 s72, s34, 2
	s_add_u32 s35, s30, 0xfff80080
	s_addc_u32 s54, s31, -1
	s_cmp_eq_u32 s21, s34
	s_cselect_b32 s55, s23, s54
	s_cselect_b32 s54, s22, s35
	s_cselect_b32 s35, s25, s71
	s_cselect_b32 s34, s24, s27
	s_add_i32 s73, 0, 0x10000
	s_add_i32 s85, 0, 0x14000
	v_add_u32_e32 v148, s73, v175
	v_add_u32_e32 v164, s85, v175
	ds_read_b128 v[136:139], v148
	ds_read_b128 v[140:143], v148 offset:1024
	ds_read_b128 v[144:147], v148 offset:2048
	ds_read_b128 v[148:151], v148 offset:3072
	ds_read_b128 v[152:155], v164
	ds_read_b128 v[156:159], v164 offset:1024
	ds_read_b128 v[160:163], v164 offset:2048
	ds_read_b128 v[164:167], v164 offset:3072
	v_lshl_add_u64 v[172:173], s[30:31], 0, v[134:135]
	s_add_i32 m0, s58, 0xc000
	ds_read_b128 v[168:171], v177
	ds_read_b128 v[178:181], v177 offset:1024
	ds_read_b128 v[182:185], v177 offset:2048
	ds_read_b128 v[186:189], v177 offset:3072
	ds_read_b128 v[190:193], v177 offset:4096
	ds_read_b128 v[210:213], v177 offset:5120
	ds_read_b128 v[214:217], v177 offset:6144
	ds_read_b128 v[218:221], v177 offset:7168
	global_load_lds_dwordx4 v[172:173], off
	v_lshl_add_u64 v[172:173], s[30:31], 0, v[132:133]
	s_add_i32 m0, s58, 0xe000
	s_nop 0
	global_load_lds_dwordx4 v[172:173], off
	s_sub_u32 s98, s30, 0x80000
	s_subb_u32 s99, s31, 0
	v_lshl_add_u64 v[172:173], s[98:99], 0, v[134:135]
	s_mov_b32 m0, s65
	s_nop 0
	global_load_lds_dwordx4 v[172:173], off
	v_lshl_add_u64 v[172:173], s[98:99], 0, v[132:133]
	s_mov_b32 m0, s66
	s_nop 0
	global_load_lds_dwordx4 v[172:173], off
	s_waitcnt vmcnt(8)
	s_waitcnt lgkmcnt(0)
	s_barrier
	v_mfma_f32_16x16x32_bf16 v[126:129], v[136:139], v[168:171], v[126:129]
	v_mfma_f32_16x16x32_bf16 v[94:97], v[144:147], v[168:171], v[94:97]
	v_mfma_f32_16x16x32_bf16 v[122:125], v[136:139], v[182:185], v[122:125]
	v_mfma_f32_16x16x32_bf16 v[90:93], v[144:147], v[182:185], v[90:93]
	v_mfma_f32_16x16x32_bf16 v[118:121], v[136:139], v[190:193], v[118:121]
	v_mfma_f32_16x16x32_bf16 v[86:89], v[144:147], v[190:193], v[86:89]
	v_mfma_f32_16x16x32_bf16 v[114:117], v[136:139], v[214:217], v[114:117]
	v_mfma_f32_16x16x32_bf16 v[82:85], v[144:147], v[214:217], v[82:85]
	v_mfma_f32_16x16x32_bf16 v[126:129], v[140:143], v[178:181], v[126:129]
	v_mfma_f32_16x16x32_bf16 v[94:97], v[148:151], v[178:181], v[94:97]
	v_mfma_f32_16x16x32_bf16 v[122:125], v[140:143], v[186:189], v[122:125]
	v_mfma_f32_16x16x32_bf16 v[90:93], v[148:151], v[186:189], v[90:93]
	v_mfma_f32_16x16x32_bf16 v[118:121], v[140:143], v[210:213], v[118:121]
	v_mfma_f32_16x16x32_bf16 v[86:89], v[148:151], v[210:213], v[86:89]
	v_mfma_f32_16x16x32_bf16 v[114:117], v[140:143], v[218:221], v[114:117]
	v_mfma_f32_16x16x32_bf16 v[82:85], v[148:151], v[218:221], v[82:85]
	v_mfma_f32_16x16x32_bf16 v[62:65], v[152:155], v[168:171], v[62:65]
	v_mfma_f32_16x16x32_bf16 v[42:45], v[160:163], v[168:171], v[42:45]
	v_mfma_f32_16x16x32_bf16 v[58:61], v[152:155], v[182:185], v[58:61]
	v_mfma_f32_16x16x32_bf16 v[34:37], v[160:163], v[182:185], v[34:37]
	v_mfma_f32_16x16x32_bf16 v[54:57], v[152:155], v[190:193], v[54:57]
	v_mfma_f32_16x16x32_bf16 v[26:29], v[160:163], v[190:193], v[26:29]
	v_mfma_f32_16x16x32_bf16 v[50:53], v[152:155], v[214:217], v[50:53]
	v_mfma_f32_16x16x32_bf16 v[18:21], v[160:163], v[214:217], v[18:21]
	v_mfma_f32_16x16x32_bf16 v[62:65], v[156:159], v[178:181], v[62:65]
	v_mfma_f32_16x16x32_bf16 v[42:45], v[164:167], v[178:181], v[42:45]
	v_mfma_f32_16x16x32_bf16 v[58:61], v[156:159], v[186:189], v[58:61]
	v_mfma_f32_16x16x32_bf16 v[34:37], v[164:167], v[186:189], v[34:37]
	v_mfma_f32_16x16x32_bf16 v[54:57], v[156:159], v[210:213], v[54:57]
	v_mfma_f32_16x16x32_bf16 v[26:29], v[164:167], v[210:213], v[26:29]
	v_mfma_f32_16x16x32_bf16 v[50:53], v[156:159], v[218:221], v[50:53]
	v_mfma_f32_16x16x32_bf16 v[18:21], v[164:167], v[218:221], v[18:21]
	s_barrier
	s_add_i32 s73, s73, s56
	v_lshl_add_u64 v[172:173], s[34:35], 0, v[0:1]
	s_mov_b32 m0, s73
	ds_read_b128 v[168:171], v177 offset:16384
	ds_read_b128 v[178:181], v177 offset:17408
	ds_read_b128 v[182:185], v177 offset:18432
	ds_read_b128 v[186:189], v177 offset:19456
	ds_read_b128 v[190:193], v177 offset:20480
	ds_read_b128 v[210:213], v177 offset:21504
	ds_read_b128 v[214:217], v177 offset:22528
	ds_read_b128 v[218:221], v177 offset:23552
	global_load_lds_dwordx4 v[172:173], off
	s_add_i32 m0, s73, 0x2000
	s_add_u32 s90, s34, 0x80000
	v_lshl_add_u64 v[194:195], s[34:35], 0, v[130:131]
	s_addc_u32 s91, s35, 0
	s_add_i32 s73, s85, s56
	global_load_lds_dwordx4 v[194:195], off
	v_lshl_add_u64 v[222:223], s[90:91], 0, v[0:1]
	s_mov_b32 m0, s73
	v_lshl_add_u64 v[224:225], s[54:55], 0, v[130:131]
	global_load_lds_dwordx4 v[222:223], off
	v_lshl_add_u64 v[222:223], s[90:91], 0, v[130:131]
	s_add_i32 m0, s73, 0x2000
	s_nop 0
	global_load_lds_dwordx4 v[222:223], off
	v_lshl_add_u64 v[222:223], s[54:55], 0, v[0:1]
	s_waitcnt vmcnt(4)
	s_waitcnt lgkmcnt(0)
	s_barrier
; #define PG8_STAGE(bufoff, gbase, voff) do { _Pragma("unroll") for (int _i = 0; _i < 2; ++_i) \
;         __builtin_amdgcn_global_load_lds((const unsigned*)((const char*)(gbase) + (voff)[_i]), (LAS unsigned*)(lds + (bufoff) + ldsw + _i * 8192), 16, 0, 0); } while (0)
; #define PG8_LDA(dst, b, h) do { _Pragma("unroll") for (int m = 0; m < 4; ++m) _Pragma("unroll") for (int k = 0; k < 2; ++k) dst[m][k] = *(const LAS bf16x8*)(lds + PG8_SA(b, h) + aoff + m * 2048 + k * 1024); } while (0)
; #define PG8_LDB(dst, b, h) do { _Pragma("unroll") for (int n = 0; n < 2; ++n) _Pragma("unroll") for (int k = 0; k < 2; ++k) dst[n][k] = *(const LAS bf16x8*)(lds + PG8_SB(b, h) + boff + n * 2048 + k * 1024); } while (0)
; #define PG8_MMA(ai, bj, At, Bt) do { __builtin_amdgcn_s_setprio(1); _Pragma("unroll") for (int m = 0; m < 4; ++m) _Pragma("unroll") for (int n = 0; n < 2; ++n) _Pragma("unroll") for (int k = 0; k < 2; ++k) \
;         acc[ai][bj][m][n] = __builtin_amdgcn_mfma_f32_16x16x32_bf16(Bt[n][k], At[m][k], acc[ai][bj][m][n], 0, 0, 0); __builtin_amdgcn_s_setprio(0); } while (0)
; #define PG8_WAIT_V(n) asm volatile("s_waitcnt vmcnt(" #n ")" ::: "memory")
; #define PG8_WAIT_L(n) asm volatile("s_waitcnt lgkmcnt(" #n ")" ::: "memory")
; #define PG8_BAR __builtin_amdgcn_s_barrier()
; #define PG8_SCHED __builtin_amdgcn_sched_barrier(0)
; template <class Epi, bool ALIGN_EPI>
; __device__ __forceinline__ void gemm_phase(LAS unsigned char* lds, const int tid, const Gemm g, const StaticOrder& S, const Epi& E) {
;     ...
;             PG8_WAIT_V(8); PG8_WAIT_L(0); PG8_BAR; PG8_MMA(1, 0, At, B0); PG8_MMA(1, 1, At, B1); PG8_BAR; PG8_SCHED;
;             PG8_LDB(B0, 1, 0); PG8_LDB(B1, 1, 1); PG8_SCHED; PG8_LDA(At, 1, 0); PG8_STAGE(PG8_SA(0, 1), a2 + hstepA, voffA);
;             PG8_WAIT_V(8); PG8_WAIT_L(0); PG8_BAR; PG8_MMA(0, 0, At, B0); PG8_MMA(0, 1, At, B1); PG8_BAR; PG8_SCHED;
	v_mfma_f32_16x16x32_bf16 v[110:113], v[136:139], v[168:171], v[110:113]
	v_mfma_f32_16x16x32_bf16 v[78:81], v[144:147], v[168:171], v[78:81]
	v_mfma_f32_16x16x32_bf16 v[106:109], v[136:139], v[182:185], v[106:109]
	v_mfma_f32_16x16x32_bf16 v[74:77], v[144:147], v[182:185], v[74:77]
	v_mfma_f32_16x16x32_bf16 v[102:105], v[136:139], v[190:193], v[102:105]
	v_mfma_f32_16x16x32_bf16 v[70:73], v[144:147], v[190:193], v[70:73]
	v_mfma_f32_16x16x32_bf16 v[98:101], v[136:139], v[214:217], v[98:101]
	v_mfma_f32_16x16x32_bf16 v[66:69], v[144:147], v[214:217], v[66:69]
	v_mfma_f32_16x16x32_bf16 v[110:113], v[140:143], v[178:181], v[110:113]
	v_mfma_f32_16x16x32_bf16 v[78:81], v[148:151], v[178:181], v[78:81]
	v_mfma_f32_16x16x32_bf16 v[106:109], v[140:143], v[186:189], v[106:109]
	v_mfma_f32_16x16x32_bf16 v[74:77], v[148:151], v[186:189], v[74:77]
	v_mfma_f32_16x16x32_bf16 v[102:105], v[140:143], v[210:213], v[102:105]
	v_mfma_f32_16x16x32_bf16 v[70:73], v[148:151], v[210:213], v[70:73]
	v_mfma_f32_16x16x32_bf16 v[98:101], v[140:143], v[218:221], v[98:101]
	v_mfma_f32_16x16x32_bf16 v[66:69], v[148:151], v[218:221], v[66:69]
	v_mfma_f32_16x16x32_bf16 v[46:49], v[152:155], v[168:171], v[46:49]
	v_mfma_f32_16x16x32_bf16 v[14:17], v[160:163], v[168:171], v[14:17]
	v_mfma_f32_16x16x32_bf16 v[38:41], v[152:155], v[182:185], v[38:41]
	v_mfma_f32_16x16x32_bf16 v[10:13], v[160:163], v[182:185], v[10:13]
	v_mfma_f32_16x16x32_bf16 v[30:33], v[152:155], v[190:193], v[30:33]
	v_mfma_f32_16x16x32_bf16 v[6:9], v[160:163], v[190:193], v[6:9]
	v_mfma_f32_16x16x32_bf16 v[22:25], v[152:155], v[214:217], v[22:25]
	v_mfma_f32_16x16x32_bf16 v[2:5], v[160:163], v[214:217], v[2:5]
	v_mfma_f32_16x16x32_bf16 v[46:49], v[156:159], v[178:181], v[46:49]
	v_mfma_f32_16x16x32_bf16 v[14:17], v[164:167], v[178:181], v[14:17]
	v_mfma_f32_16x16x32_bf16 v[38:41], v[156:159], v[186:189], v[38:41]
	v_mfma_f32_16x16x32_bf16 v[10:13], v[164:167], v[186:189], v[10:13]
	v_mfma_f32_16x16x32_bf16 v[30:33], v[156:159], v[210:213], v[30:33]
	v_mfma_f32_16x16x32_bf16 v[6:9], v[164:167], v[210:213], v[6:9]
	v_mfma_f32_16x16x32_bf16 v[22:25], v[156:159], v[218:221], v[22:25]
	v_mfma_f32_16x16x32_bf16 v[2:5], v[164:167], v[218:221], v[2:5]
	s_barrier
	s_add_i32 s73, 0, 0x18000
	s_add_i32 s85, 0, 0x1c000
	v_add_u32_e32 v148, s73, v175
	v_add_u32_e32 v164, s85, v175
	ds_read_b128 v[136:139], v148
	ds_read_b128 v[140:143], v148 offset:1024
	ds_read_b128 v[144:147], v148 offset:2048
	ds_read_b128 v[148:151], v148 offset:3072
	ds_read_b128 v[152:155], v164
	ds_read_b128 v[156:159], v164 offset:1024
	ds_read_b128 v[160:163], v164 offset:2048
	ds_read_b128 v[164:167], v164 offset:3072
	s_mov_b32 m0, s58
	s_nop 0
	global_load_lds_dwordx4 v[222:223], off
	s_mov_b32 m0, s60
	s_nop 0
	global_load_lds_dwordx4 v[224:225], off
	s_add_u32 s54, s54, 0x80000
	s_addc_u32 s55, s55, 0
	s_mov_b32 m0, s61
	v_lshl_add_u64 v[240:241], s[54:55], 0, v[0:1]
	ds_read_b128 v[168:171], v177 offset:32768
	ds_read_b128 v[178:181], v177 offset:33792
	ds_read_b128 v[182:185], v177 offset:34816
	ds_read_b128 v[186:189], v177 offset:35840
	ds_read_b128 v[190:193], v177 offset:36864
	ds_read_b128 v[210:213], v177 offset:37888
	ds_read_b128 v[214:217], v177 offset:38912
	ds_read_b128 v[218:221], v177 offset:39936
	global_load_lds_dwordx4 v[240:241], off
	v_lshl_add_u64 v[240:241], s[54:55], 0, v[130:131]
	s_mov_b32 m0, s62
	s_nop 0
	global_load_lds_dwordx4 v[240:241], off
	s_waitcnt vmcnt(8)
	s_waitcnt lgkmcnt(0)
	s_barrier
; #define PG8_STAGE(bufoff, gbase, voff) do { _Pragma("unroll") for (int _i = 0; _i < 2; ++_i) \
;         __builtin_amdgcn_global_load_lds((const unsigned*)((const char*)(gbase) + (voff)[_i]), (LAS unsigned*)(lds + (bufoff) + ldsw + _i * 8192), 16, 0, 0); } while (0)
; #define PG8_LDA(dst, b, h) do { _Pragma("unroll") for (int m = 0; m < 4; ++m) _Pragma("unroll") for (int k = 0; k < 2; ++k) dst[m][k] = *(const LAS bf16x8*)(lds + PG8_SA(b, h) + aoff + m * 2048 + k * 1024); } while (0)
; #define PG8_MMA(ai, bj, At, Bt) do { __builtin_amdgcn_s_setprio(1); _Pragma("unroll") for (int m = 0; m < 4; ++m) _Pragma("unroll") for (int n = 0; n < 2; ++n) _Pragma("unroll") for (int k = 0; k < 2; ++k) \
;         acc[ai][bj][m][n] = __builtin_amdgcn_mfma_f32_16x16x32_bf16(Bt[n][k], At[m][k], acc[ai][bj][m][n], 0, 0, 0); __builtin_amdgcn_s_setprio(0); } while (0)
; #define PG8_WAIT_V(n) asm volatile("s_waitcnt vmcnt(" #n ")" ::: "memory")
; #define PG8_WAIT_L(n) asm volatile("s_waitcnt lgkmcnt(" #n ")" ::: "memory")
; #define PG8_BAR __builtin_amdgcn_s_barrier()
; #define PG8_SCHED __builtin_amdgcn_sched_barrier(0)
; template <class Epi, bool ALIGN_EPI>
; __device__ __forceinline__ void gemm_phase(LAS unsigned char* lds, const int tid, const Gemm g, const StaticOrder& S, const Epi& E) {
;     ...
;             PG8_WAIT_V(8); PG8_WAIT_L(0); PG8_BAR; PG8_MMA(0, 0, At, B0); PG8_MMA(0, 1, At, B1); PG8_BAR; PG8_SCHED;
;             PG8_LDA(At, 1, 1); PG8_STAGE(PG8_SB(1, 0), b3, voffB); PG8_STAGE(PG8_SB(1, 1), b3 + hstepB, voffB); PG8_STAGE(PG8_SA(1, 0), a3, voffA);
;             PG8_WAIT_V(8); PG8_WAIT_L(0); PG8_BAR; PG8_MMA(1, 0, At, B0); PG8_MMA(1, 1, At, B1); PG8_BAR; PG8_SCHED;
;         }
;         if constexpr (ALIGN_EPI) { if (wr == 0) PG8_BAR; }
;         E(acc, cur, wr, wc, fr, fq);
	v_mfma_f32_16x16x32_bf16 v[126:129], v[136:139], v[168:171], v[126:129]
	v_mfma_f32_16x16x32_bf16 v[94:97], v[144:147], v[168:171], v[94:97]
	v_mfma_f32_16x16x32_bf16 v[122:125], v[136:139], v[182:185], v[122:125]
	v_mfma_f32_16x16x32_bf16 v[90:93], v[144:147], v[182:185], v[90:93]
	v_mfma_f32_16x16x32_bf16 v[118:121], v[136:139], v[190:193], v[118:121]
	v_mfma_f32_16x16x32_bf16 v[86:89], v[144:147], v[190:193], v[86:89]
	v_mfma_f32_16x16x32_bf16 v[114:117], v[136:139], v[214:217], v[114:117]
	v_mfma_f32_16x16x32_bf16 v[82:85], v[144:147], v[214:217], v[82:85]
	v_mfma_f32_16x16x32_bf16 v[126:129], v[140:143], v[178:181], v[126:129]
	v_mfma_f32_16x16x32_bf16 v[94:97], v[148:151], v[178:181], v[94:97]
	v_mfma_f32_16x16x32_bf16 v[122:125], v[140:143], v[186:189], v[122:125]
	v_mfma_f32_16x16x32_bf16 v[90:93], v[148:151], v[186:189], v[90:93]
	v_mfma_f32_16x16x32_bf16 v[118:121], v[140:143], v[210:213], v[118:121]
	v_mfma_f32_16x16x32_bf16 v[86:89], v[148:151], v[210:213], v[86:89]
	v_mfma_f32_16x16x32_bf16 v[114:117], v[140:143], v[218:221], v[114:117]
	v_mfma_f32_16x16x32_bf16 v[82:85], v[148:151], v[218:221], v[82:85]
	v_mfma_f32_16x16x32_bf16 v[62:65], v[152:155], v[168:171], v[62:65]
	v_mfma_f32_16x16x32_bf16 v[42:45], v[160:163], v[168:171], v[42:45]
	v_mfma_f32_16x16x32_bf16 v[58:61], v[152:155], v[182:185], v[58:61]
	v_mfma_f32_16x16x32_bf16 v[34:37], v[160:163], v[182:185], v[34:37]
	v_mfma_f32_16x16x32_bf16 v[54:57], v[152:155], v[190:193], v[54:57]
	v_mfma_f32_16x16x32_bf16 v[26:29], v[160:163], v[190:193], v[26:29]
	v_mfma_f32_16x16x32_bf16 v[50:53], v[152:155], v[214:217], v[50:53]
	v_mfma_f32_16x16x32_bf16 v[18:21], v[160:163], v[214:217], v[18:21]
	v_mfma_f32_16x16x32_bf16 v[62:65], v[156:159], v[178:181], v[62:65]
	v_mfma_f32_16x16x32_bf16 v[42:45], v[164:167], v[178:181], v[42:45]
	v_mfma_f32_16x16x32_bf16 v[58:61], v[156:159], v[186:189], v[58:61]
	v_mfma_f32_16x16x32_bf16 v[34:37], v[164:167], v[186:189], v[34:37]
	v_mfma_f32_16x16x32_bf16 v[54:57], v[156:159], v[210:213], v[54:57]
	v_mfma_f32_16x16x32_bf16 v[26:29], v[164:167], v[210:213], v[26:29]
	v_mfma_f32_16x16x32_bf16 v[50:53], v[156:159], v[218:221], v[50:53]
	v_mfma_f32_16x16x32_bf16 v[18:21], v[164:167], v[218:221], v[18:21]
	s_barrier
	s_add_i32 s54, s73, s56
	v_lshl_add_u64 v[172:173], v[172:173], 0, s[42:43]
	s_mov_b32 m0, s54
	ds_read_b128 v[168:171], v177 offset:49152
	ds_read_b128 v[178:181], v177 offset:50176
	ds_read_b128 v[182:185], v177 offset:51200
	ds_read_b128 v[186:189], v177 offset:52224
	ds_read_b128 v[190:193], v177 offset:53248
	ds_read_b128 v[210:213], v177 offset:54272
	ds_read_b128 v[214:217], v177 offset:55296
	ds_read_b128 v[218:221], v177 offset:56320
	global_load_lds_dwordx4 v[172:173], off
	s_add_i32 m0, s54, 0x2000
	s_add_u32 s34, s34, 0x80080
	v_lshl_add_u64 v[172:173], v[194:195], 0, s[42:43]
	s_addc_u32 s35, s35, 0
	s_add_i32 s54, s85, s56
	global_load_lds_dwordx4 v[172:173], off
	v_lshl_add_u64 v[172:173], s[34:35], 0, v[0:1]
	s_mov_b32 m0, s54
	s_nop 0
	global_load_lds_dwordx4 v[172:173], off
	v_lshl_add_u64 v[172:173], s[34:35], 0, v[130:131]
	s_add_i32 m0, s54, 0x2000
	s_nop 0
	global_load_lds_dwordx4 v[172:173], off
	s_waitcnt vmcnt(4)
	s_waitcnt lgkmcnt(0)
	s_barrier
	v_mfma_f32_16x16x32_bf16 v[110:113], v[136:139], v[168:171], v[110:113]
	v_mfma_f32_16x16x32_bf16 v[78:81], v[144:147], v[168:171], v[78:81]
	v_mfma_f32_16x16x32_bf16 v[106:109], v[136:139], v[182:185], v[106:109]
	v_mfma_f32_16x16x32_bf16 v[74:77], v[144:147], v[182:185], v[74:77]
	v_mfma_f32_16x16x32_bf16 v[102:105], v[136:139], v[190:193], v[102:105]
	v_mfma_f32_16x16x32_bf16 v[70:73], v[144:147], v[190:193], v[70:73]
	v_mfma_f32_16x16x32_bf16 v[98:101], v[136:139], v[214:217], v[98:101]
	v_mfma_f32_16x16x32_bf16 v[66:69], v[144:147], v[214:217], v[66:69]
	v_mfma_f32_16x16x32_bf16 v[110:113], v[140:143], v[178:181], v[110:113]
	v_mfma_f32_16x16x32_bf16 v[78:81], v[148:151], v[178:181], v[78:81]
	v_mfma_f32_16x16x32_bf16 v[106:109], v[140:143], v[186:189], v[106:109]
	v_mfma_f32_16x16x32_bf16 v[74:77], v[148:151], v[186:189], v[74:77]
	v_mfma_f32_16x16x32_bf16 v[102:105], v[140:143], v[210:213], v[102:105]
	v_mfma_f32_16x16x32_bf16 v[70:73], v[148:151], v[210:213], v[70:73]
	v_mfma_f32_16x16x32_bf16 v[98:101], v[140:143], v[218:221], v[98:101]
	v_mfma_f32_16x16x32_bf16 v[66:69], v[148:151], v[218:221], v[66:69]
	v_mfma_f32_16x16x32_bf16 v[46:49], v[152:155], v[168:171], v[46:49]
	v_mfma_f32_16x16x32_bf16 v[14:17], v[160:163], v[168:171], v[14:17]
	v_mfma_f32_16x16x32_bf16 v[38:41], v[152:155], v[182:185], v[38:41]
	v_mfma_f32_16x16x32_bf16 v[10:13], v[160:163], v[182:185], v[10:13]
	v_mfma_f32_16x16x32_bf16 v[30:33], v[152:155], v[190:193], v[30:33]
	v_mfma_f32_16x16x32_bf16 v[6:9], v[160:163], v[190:193], v[6:9]
	v_mfma_f32_16x16x32_bf16 v[22:25], v[152:155], v[214:217], v[22:25]
	v_mfma_f32_16x16x32_bf16 v[2:5], v[160:163], v[214:217], v[2:5]
	v_mfma_f32_16x16x32_bf16 v[46:49], v[156:159], v[178:181], v[46:49]
	v_mfma_f32_16x16x32_bf16 v[14:17], v[164:167], v[178:181], v[14:17]
	v_mfma_f32_16x16x32_bf16 v[38:41], v[156:159], v[186:189], v[38:41]
	v_mfma_f32_16x16x32_bf16 v[10:13], v[164:167], v[186:189], v[10:13]
	v_mfma_f32_16x16x32_bf16 v[30:33], v[156:159], v[210:213], v[30:33]
	v_mfma_f32_16x16x32_bf16 v[6:9], v[164:167], v[210:213], v[6:9]
	v_mfma_f32_16x16x32_bf16 v[22:25], v[156:159], v[218:221], v[22:25]
	v_mfma_f32_16x16x32_bf16 v[2:5], v[164:167], v[218:221], v[2:5]
	s_barrier
	s_add_u32 s27, s27, 0x100
	s_addc_u32 s71, s71, 0
	s_add_u32 s30, s30, 0x100
	s_addc_u32 s31, s31, 0
	s_cmp_ge_u32 s72, s19
	s_mov_b32 s34, s72
	s_cbranch_scc0 .LBB0_209
	s_setprio 1
	s_and_b64 vcc, exec, s[16:17]
	s_cbranch_vccz .LBB0_212
	s_barrier
	s_setprio 0

; #define PG8_BAR __builtin_amdgcn_s_barrier()
; template <class Epi, bool ALIGN_EPI>
; __device__ __forceinline__ void gemm_phase(LAS unsigned char* lds, const int tid, const Gemm g, const StaticOrder& S, const Epi& E) {
;     ...
;         if constexpr (ALIGN_EPI) { if (wr == 0) PG8_BAR; }
;         E(acc, cur, wr, wc, fr, fq);
.Lwin_nobias:
	s_setprio 1
	s_and_b64 vcc, exec, s[8:9]
	s_cbranch_vccz .LBB0_670
	s_barrier
	s_setprio 0
